# prep mod-GEMV item: silu staging loop no longer waits per load (36 loads issued, counted waits)
# speedup vs baseline: 1.1829x; 1.0074x over previous
; DI float siluf_(float z) { return z / (1.f + __expf(-z)); }
; DI void ph_prep(const Params& p, unsigned char* smem, int bid, int nb) {
;     ...
;       for (int e = tid; e < 9 * 1024; e += 256) {
;         const int rr = e >> 10, k = e & 1023;
;         const float v = rr < 8 ? p.c[rr * 1024 + k] : p.c_ctx[k];
;         sc[e] = siluf_(v);
;       }
.LBB0_45:
	s_and_b64 vcc, exec, s[10:11]
	s_cbranch_vccz .LBB0_55
	s_barrier
	s_mov_b64 s[10:11], exec
	v_readlane_b32 s12, v253, 54
	v_readlane_b32 s13, v253, 55
	v_readlane_b32 s52, v253, 7
	s_and_b64 s[12:13], s[10:11], s[12:13]
	v_readlane_b32 s58, v253, 13
	v_readlane_b32 s59, v253, 14
	v_readlane_b32 s53, v253, 8
	v_readlane_b32 s54, v253, 9
	v_readlane_b32 s55, v253, 10
	v_readlane_b32 s56, v253, 11
	v_readlane_b32 s57, v253, 12
	v_readlane_b32 s60, v253, 15
	v_readlane_b32 s61, v253, 16
	v_readlane_b32 s62, v253, 17
	v_readlane_b32 s63, v253, 18
	v_readlane_b32 s64, v253, 19
	v_readlane_b32 s65, v253, 20
	v_readlane_b32 s66, v253, 21
	v_readlane_b32 s67, v253, 22
	s_mov_b64 exec, s[12:13]
	s_cbranch_execz .LBB0_49
	v_mov_b64_e32 v[0:1], v[58:59]
	v_mov_b32_e32 v2, v131
	v_lshlrev_b32_e32 v48, 2, v44
	s_mov_b64 s[88:89], 0x1000
	global_load_dword v196, v[0:1], off
	global_load_dword v197, v[0:1], off offset:1024
	global_load_dword v198, v[0:1], off offset:2048
	global_load_dword v199, v[0:1], off offset:3072
	v_lshl_add_u64 v[0:1], v[0:1], 0, s[88:89]
	global_load_dword v200, v[0:1], off
	global_load_dword v201, v[0:1], off offset:1024
	global_load_dword v202, v[0:1], off offset:2048
	global_load_dword v203, v[0:1], off offset:3072
	v_lshl_add_u64 v[0:1], v[0:1], 0, s[88:89]
	global_load_dword v204, v[0:1], off
	global_load_dword v205, v[0:1], off offset:1024
	global_load_dword v206, v[0:1], off offset:2048
	global_load_dword v207, v[0:1], off offset:3072
	v_lshl_add_u64 v[0:1], v[0:1], 0, s[88:89]
	global_load_dword v208, v[0:1], off
	global_load_dword v209, v[0:1], off offset:1024
	global_load_dword v210, v[0:1], off offset:2048
	global_load_dword v211, v[0:1], off offset:3072
	v_lshl_add_u64 v[0:1], v[0:1], 0, s[88:89]
	global_load_dword v212, v[0:1], off
	global_load_dword v213, v[0:1], off offset:1024
	global_load_dword v214, v[0:1], off offset:2048
	global_load_dword v215, v[0:1], off offset:3072
	v_lshl_add_u64 v[0:1], v[0:1], 0, s[88:89]
	global_load_dword v216, v[0:1], off
	global_load_dword v217, v[0:1], off offset:1024
	global_load_dword v218, v[0:1], off offset:2048
	global_load_dword v219, v[0:1], off offset:3072
	v_lshl_add_u64 v[0:1], v[0:1], 0, s[88:89]
	global_load_dword v220, v[0:1], off
	global_load_dword v221, v[0:1], off offset:1024
	global_load_dword v222, v[0:1], off offset:2048
	global_load_dword v223, v[0:1], off offset:3072
	v_lshl_add_u64 v[0:1], v[0:1], 0, s[88:89]
	global_load_dword v224, v[0:1], off
	global_load_dword v225, v[0:1], off offset:1024
	global_load_dword v226, v[0:1], off offset:2048
	global_load_dword v227, v[0:1], off offset:3072
	global_load_dword v228, v48, s[58:59]
	global_load_dword v229, v48, s[58:59] offset:1024
	global_load_dword v230, v48, s[58:59] offset:2048
	global_load_dword v231, v48, s[58:59] offset:3072
	s_waitcnt vmcnt(35)
	v_mul_f32_e32 v5, 0xbfb8aa3b, v196
	v_exp_f32_e32 v5, v5
	s_nop 0
	v_add_f32_e32 v5, 1.0, v5
	v_div_scale_f32 v6, s[88:89], v5, v5, v196
	v_rcp_f32_e32 v7, v6
	v_div_scale_f32 v8, vcc, v196, v5, v196
	v_fma_f32 v9, -v6, v7, 1.0
	v_fmac_f32_e32 v7, v9, v7
	v_mul_f32_e32 v9, v8, v7
	v_fma_f32 v10, -v6, v9, v8
	v_fmac_f32_e32 v9, v10, v7
	v_fma_f32 v6, -v6, v9, v8
	v_div_fmas_f32 v6, v6, v7, v9
	v_div_fixup_f32 v4, v6, v5, v196
	ds_write_b32 v2, v4
	s_waitcnt vmcnt(34)
	v_mul_f32_e32 v5, 0xbfb8aa3b, v197
	v_exp_f32_e32 v5, v5
	s_nop 0
	v_add_f32_e32 v5, 1.0, v5
	v_div_scale_f32 v6, s[88:89], v5, v5, v197
	v_rcp_f32_e32 v7, v6
	v_div_scale_f32 v8, vcc, v197, v5, v197
	v_fma_f32 v9, -v6, v7, 1.0
	v_fmac_f32_e32 v7, v9, v7
	v_mul_f32_e32 v9, v8, v7
	v_fma_f32 v10, -v6, v9, v8
	v_fmac_f32_e32 v9, v10, v7
	v_fma_f32 v6, -v6, v9, v8
	v_div_fmas_f32 v6, v6, v7, v9
	v_div_fixup_f32 v4, v6, v5, v197
	ds_write_b32 v2, v4 offset:1024
	s_waitcnt vmcnt(33)
	v_mul_f32_e32 v5, 0xbfb8aa3b, v198
	v_exp_f32_e32 v5, v5
	s_nop 0
	v_add_f32_e32 v5, 1.0, v5
	v_div_scale_f32 v6, s[88:89], v5, v5, v198
	v_rcp_f32_e32 v7, v6
	v_div_scale_f32 v8, vcc, v198, v5, v198
	v_fma_f32 v9, -v6, v7, 1.0
	v_fmac_f32_e32 v7, v9, v7
	v_mul_f32_e32 v9, v8, v7
	v_fma_f32 v10, -v6, v9, v8
	v_fmac_f32_e32 v9, v10, v7
	v_fma_f32 v6, -v6, v9, v8
	v_div_fmas_f32 v6, v6, v7, v9
	v_div_fixup_f32 v4, v6, v5, v198
	ds_write_b32 v2, v4 offset:2048
	s_waitcnt vmcnt(32)
	v_mul_f32_e32 v5, 0xbfb8aa3b, v199
	v_exp_f32_e32 v5, v5
	s_nop 0
	v_add_f32_e32 v5, 1.0, v5
	v_div_scale_f32 v6, s[88:89], v5, v5, v199
	v_rcp_f32_e32 v7, v6
	v_div_scale_f32 v8, vcc, v199, v5, v199
	v_fma_f32 v9, -v6, v7, 1.0
	v_fmac_f32_e32 v7, v9, v7
	v_mul_f32_e32 v9, v8, v7
	v_fma_f32 v10, -v6, v9, v8
	v_fmac_f32_e32 v9, v10, v7
	v_fma_f32 v6, -v6, v9, v8
	v_div_fmas_f32 v6, v6, v7, v9
	v_div_fixup_f32 v4, v6, v5, v199
	ds_write_b32 v2, v4 offset:3072
	s_waitcnt vmcnt(31)
	v_mul_f32_e32 v5, 0xbfb8aa3b, v200
	v_exp_f32_e32 v5, v5
	s_nop 0
	v_add_f32_e32 v5, 1.0, v5
	v_div_scale_f32 v6, s[88:89], v5, v5, v200
	v_rcp_f32_e32 v7, v6
	v_div_scale_f32 v8, vcc, v200, v5, v200
	v_fma_f32 v9, -v6, v7, 1.0
	v_fmac_f32_e32 v7, v9, v7
	v_mul_f32_e32 v9, v8, v7
	v_fma_f32 v10, -v6, v9, v8
	v_fmac_f32_e32 v9, v10, v7
	v_fma_f32 v6, -v6, v9, v8
	v_div_fmas_f32 v6, v6, v7, v9
	v_div_fixup_f32 v4, v6, v5, v200
	ds_write_b32 v2, v4 offset:4096
	s_waitcnt vmcnt(30)
	v_mul_f32_e32 v5, 0xbfb8aa3b, v201
	v_exp_f32_e32 v5, v5
	s_nop 0
	v_add_f32_e32 v5, 1.0, v5
	v_div_scale_f32 v6, s[88:89], v5, v5, v201
	v_rcp_f32_e32 v7, v6
	v_div_scale_f32 v8, vcc, v201, v5, v201
	v_fma_f32 v9, -v6, v7, 1.0
	v_fmac_f32_e32 v7, v9, v7
	v_mul_f32_e32 v9, v8, v7
	v_fma_f32 v10, -v6, v9, v8
	v_fmac_f32_e32 v9, v10, v7
	v_fma_f32 v6, -v6, v9, v8
	v_div_fmas_f32 v6, v6, v7, v9
	v_div_fixup_f32 v4, v6, v5, v201
	ds_write_b32 v2, v4 offset:5120
	s_waitcnt vmcnt(29)
; DI float siluf_(float z) { return z / (1.f + __expf(-z)); }
; DI void ph_prep(const Params& p, unsigned char* smem, int bid, int nb) {
;     ...
;       for (int e = tid; e < 9 * 1024; e += 256) {
;         const int rr = e >> 10, k = e & 1023;
;         const float v = rr < 8 ? p.c[rr * 1024 + k] : p.c_ctx[k];
;         sc[e] = siluf_(v);
;       }
	v_mul_f32_e32 v5, 0xbfb8aa3b, v202
	v_exp_f32_e32 v5, v5
	s_nop 0
	v_add_f32_e32 v5, 1.0, v5
	v_div_scale_f32 v6, s[88:89], v5, v5, v202
	v_rcp_f32_e32 v7, v6
	v_div_scale_f32 v8, vcc, v202, v5, v202
	v_fma_f32 v9, -v6, v7, 1.0
	v_fmac_f32_e32 v7, v9, v7
	v_mul_f32_e32 v9, v8, v7
	v_fma_f32 v10, -v6, v9, v8
	v_fmac_f32_e32 v9, v10, v7
	v_fma_f32 v6, -v6, v9, v8
	v_div_fmas_f32 v6, v6, v7, v9
	v_div_fixup_f32 v4, v6, v5, v202
	ds_write_b32 v2, v4 offset:6144
	s_waitcnt vmcnt(28)
	v_mul_f32_e32 v5, 0xbfb8aa3b, v203
	v_exp_f32_e32 v5, v5
	s_nop 0
	v_add_f32_e32 v5, 1.0, v5
	v_div_scale_f32 v6, s[88:89], v5, v5, v203
	v_rcp_f32_e32 v7, v6
	v_div_scale_f32 v8, vcc, v203, v5, v203
	v_fma_f32 v9, -v6, v7, 1.0
	v_fmac_f32_e32 v7, v9, v7
	v_mul_f32_e32 v9, v8, v7
	v_fma_f32 v10, -v6, v9, v8
	v_fmac_f32_e32 v9, v10, v7
	v_fma_f32 v6, -v6, v9, v8
	v_div_fmas_f32 v6, v6, v7, v9
	v_div_fixup_f32 v4, v6, v5, v203
	ds_write_b32 v2, v4 offset:7168
	s_waitcnt vmcnt(27)
	v_mul_f32_e32 v5, 0xbfb8aa3b, v204
	v_exp_f32_e32 v5, v5
	s_nop 0
	v_add_f32_e32 v5, 1.0, v5
	v_div_scale_f32 v6, s[88:89], v5, v5, v204
	v_rcp_f32_e32 v7, v6
	v_div_scale_f32 v8, vcc, v204, v5, v204
	v_fma_f32 v9, -v6, v7, 1.0
	v_fmac_f32_e32 v7, v9, v7
	v_mul_f32_e32 v9, v8, v7
	v_fma_f32 v10, -v6, v9, v8
	v_fmac_f32_e32 v9, v10, v7
	v_fma_f32 v6, -v6, v9, v8
	v_div_fmas_f32 v6, v6, v7, v9
	v_div_fixup_f32 v4, v6, v5, v204
	ds_write_b32 v2, v4 offset:8192
	s_waitcnt vmcnt(26)
	v_mul_f32_e32 v5, 0xbfb8aa3b, v205
	v_exp_f32_e32 v5, v5
	s_nop 0
	v_add_f32_e32 v5, 1.0, v5
	v_div_scale_f32 v6, s[88:89], v5, v5, v205
	v_rcp_f32_e32 v7, v6
	v_div_scale_f32 v8, vcc, v205, v5, v205
	v_fma_f32 v9, -v6, v7, 1.0
	v_fmac_f32_e32 v7, v9, v7
	v_mul_f32_e32 v9, v8, v7
	v_fma_f32 v10, -v6, v9, v8
	v_fmac_f32_e32 v9, v10, v7
	v_fma_f32 v6, -v6, v9, v8
	v_div_fmas_f32 v6, v6, v7, v9
	v_div_fixup_f32 v4, v6, v5, v205
	ds_write_b32 v2, v4 offset:9216
	s_waitcnt vmcnt(25)
	v_mul_f32_e32 v5, 0xbfb8aa3b, v206
	v_exp_f32_e32 v5, v5
	s_nop 0
	v_add_f32_e32 v5, 1.0, v5
	v_div_scale_f32 v6, s[88:89], v5, v5, v206
	v_rcp_f32_e32 v7, v6
	v_div_scale_f32 v8, vcc, v206, v5, v206
	v_fma_f32 v9, -v6, v7, 1.0
	v_fmac_f32_e32 v7, v9, v7
	v_mul_f32_e32 v9, v8, v7
	v_fma_f32 v10, -v6, v9, v8
	v_fmac_f32_e32 v9, v10, v7
	v_fma_f32 v6, -v6, v9, v8
	v_div_fmas_f32 v6, v6, v7, v9
	v_div_fixup_f32 v4, v6, v5, v206
	ds_write_b32 v2, v4 offset:10240
	s_waitcnt vmcnt(24)
	v_mul_f32_e32 v5, 0xbfb8aa3b, v207
	v_exp_f32_e32 v5, v5
	s_nop 0
	v_add_f32_e32 v5, 1.0, v5
	v_div_scale_f32 v6, s[88:89], v5, v5, v207
	v_rcp_f32_e32 v7, v6
	v_div_scale_f32 v8, vcc, v207, v5, v207
	v_fma_f32 v9, -v6, v7, 1.0
	v_fmac_f32_e32 v7, v9, v7
	v_mul_f32_e32 v9, v8, v7
	v_fma_f32 v10, -v6, v9, v8
	v_fmac_f32_e32 v9, v10, v7
	v_fma_f32 v6, -v6, v9, v8
	v_div_fmas_f32 v6, v6, v7, v9
	v_div_fixup_f32 v4, v6, v5, v207
	ds_write_b32 v2, v4 offset:11264
	s_waitcnt vmcnt(23)
	v_mul_f32_e32 v5, 0xbfb8aa3b, v208
	v_exp_f32_e32 v5, v5
	s_nop 0
	v_add_f32_e32 v5, 1.0, v5
	v_div_scale_f32 v6, s[88:89], v5, v5, v208
	v_rcp_f32_e32 v7, v6
	v_div_scale_f32 v8, vcc, v208, v5, v208
	v_fma_f32 v9, -v6, v7, 1.0
	v_fmac_f32_e32 v7, v9, v7
	v_mul_f32_e32 v9, v8, v7
	v_fma_f32 v10, -v6, v9, v8
	v_fmac_f32_e32 v9, v10, v7
	v_fma_f32 v6, -v6, v9, v8
	v_div_fmas_f32 v6, v6, v7, v9
	v_div_fixup_f32 v4, v6, v5, v208
	ds_write_b32 v2, v4 offset:12288
	s_waitcnt vmcnt(22)
	v_mul_f32_e32 v5, 0xbfb8aa3b, v209
	v_exp_f32_e32 v5, v5
	s_nop 0
	v_add_f32_e32 v5, 1.0, v5
	v_div_scale_f32 v6, s[88:89], v5, v5, v209
	v_rcp_f32_e32 v7, v6
	v_div_scale_f32 v8, vcc, v209, v5, v209
	v_fma_f32 v9, -v6, v7, 1.0
	v_fmac_f32_e32 v7, v9, v7
	v_mul_f32_e32 v9, v8, v7
	v_fma_f32 v10, -v6, v9, v8
	v_fmac_f32_e32 v9, v10, v7
	v_fma_f32 v6, -v6, v9, v8
	v_div_fmas_f32 v6, v6, v7, v9
	v_div_fixup_f32 v4, v6, v5, v209
	ds_write_b32 v2, v4 offset:13312
	s_waitcnt vmcnt(21)
	v_mul_f32_e32 v5, 0xbfb8aa3b, v210
	v_exp_f32_e32 v5, v5
	s_nop 0
	v_add_f32_e32 v5, 1.0, v5
	v_div_scale_f32 v6, s[88:89], v5, v5, v210
	v_rcp_f32_e32 v7, v6
	v_div_scale_f32 v8, vcc, v210, v5, v210
	v_fma_f32 v9, -v6, v7, 1.0
	v_fmac_f32_e32 v7, v9, v7
	v_mul_f32_e32 v9, v8, v7
	v_fma_f32 v10, -v6, v9, v8
	v_fmac_f32_e32 v9, v10, v7
	v_fma_f32 v6, -v6, v9, v8
	v_div_fmas_f32 v6, v6, v7, v9
	v_div_fixup_f32 v4, v6, v5, v210
	ds_write_b32 v2, v4 offset:14336
	s_waitcnt vmcnt(20)
	v_mul_f32_e32 v5, 0xbfb8aa3b, v211
	v_exp_f32_e32 v5, v5
	s_nop 0
	v_add_f32_e32 v5, 1.0, v5
	v_div_scale_f32 v6, s[88:89], v5, v5, v211
	v_rcp_f32_e32 v7, v6
	v_div_scale_f32 v8, vcc, v211, v5, v211
	v_fma_f32 v9, -v6, v7, 1.0
	v_fmac_f32_e32 v7, v9, v7
	v_mul_f32_e32 v9, v8, v7
	v_fma_f32 v10, -v6, v9, v8
	v_fmac_f32_e32 v9, v10, v7
	v_fma_f32 v6, -v6, v9, v8
	v_div_fmas_f32 v6, v6, v7, v9
	v_div_fixup_f32 v4, v6, v5, v211
	ds_write_b32 v2, v4 offset:15360
	s_waitcnt vmcnt(19)
	v_mul_f32_e32 v5, 0xbfb8aa3b, v212
	v_exp_f32_e32 v5, v5
	s_nop 0
	v_add_f32_e32 v5, 1.0, v5
	v_div_scale_f32 v6, s[88:89], v5, v5, v212
	v_rcp_f32_e32 v7, v6
	v_div_scale_f32 v8, vcc, v212, v5, v212
	v_fma_f32 v9, -v6, v7, 1.0
	v_fmac_f32_e32 v7, v9, v7
	v_mul_f32_e32 v9, v8, v7
	v_fma_f32 v10, -v6, v9, v8
	v_fmac_f32_e32 v9, v10, v7
	v_fma_f32 v6, -v6, v9, v8
	v_div_fmas_f32 v6, v6, v7, v9
	v_div_fixup_f32 v4, v6, v5, v212
	ds_write_b32 v2, v4 offset:16384
	s_waitcnt vmcnt(18)
	v_mul_f32_e32 v5, 0xbfb8aa3b, v213
	v_exp_f32_e32 v5, v5
	s_nop 0
	v_add_f32_e32 v5, 1.0, v5
	v_div_scale_f32 v6, s[88:89], v5, v5, v213
	v_rcp_f32_e32 v7, v6
	v_div_scale_f32 v8, vcc, v213, v5, v213
	v_fma_f32 v9, -v6, v7, 1.0
	v_fmac_f32_e32 v7, v9, v7
	v_mul_f32_e32 v9, v8, v7
	v_fma_f32 v10, -v6, v9, v8
	v_fmac_f32_e32 v9, v10, v7
	v_fma_f32 v6, -v6, v9, v8
	v_div_fmas_f32 v6, v6, v7, v9
	v_div_fixup_f32 v4, v6, v5, v213
	ds_write_b32 v2, v4 offset:17408
	s_waitcnt vmcnt(17)
; DI float siluf_(float z) { return z / (1.f + __expf(-z)); }
; DI void ph_prep(const Params& p, unsigned char* smem, int bid, int nb) {
;     ...
;       for (int e = tid; e < 9 * 1024; e += 256) {
;         const int rr = e >> 10, k = e & 1023;
;         const float v = rr < 8 ? p.c[rr * 1024 + k] : p.c_ctx[k];
;         sc[e] = siluf_(v);
;       }
	v_mul_f32_e32 v5, 0xbfb8aa3b, v214
	v_exp_f32_e32 v5, v5
	s_nop 0
	v_add_f32_e32 v5, 1.0, v5
	v_div_scale_f32 v6, s[88:89], v5, v5, v214
	v_rcp_f32_e32 v7, v6
	v_div_scale_f32 v8, vcc, v214, v5, v214
	v_fma_f32 v9, -v6, v7, 1.0
	v_fmac_f32_e32 v7, v9, v7
	v_mul_f32_e32 v9, v8, v7
	v_fma_f32 v10, -v6, v9, v8
	v_fmac_f32_e32 v9, v10, v7
	v_fma_f32 v6, -v6, v9, v8
	v_div_fmas_f32 v6, v6, v7, v9
	v_div_fixup_f32 v4, v6, v5, v214
	ds_write_b32 v2, v4 offset:18432
	s_waitcnt vmcnt(16)
	v_mul_f32_e32 v5, 0xbfb8aa3b, v215
	v_exp_f32_e32 v5, v5
	s_nop 0
	v_add_f32_e32 v5, 1.0, v5
	v_div_scale_f32 v6, s[88:89], v5, v5, v215
	v_rcp_f32_e32 v7, v6
	v_div_scale_f32 v8, vcc, v215, v5, v215
	v_fma_f32 v9, -v6, v7, 1.0
	v_fmac_f32_e32 v7, v9, v7
	v_mul_f32_e32 v9, v8, v7
	v_fma_f32 v10, -v6, v9, v8
	v_fmac_f32_e32 v9, v10, v7
	v_fma_f32 v6, -v6, v9, v8
	v_div_fmas_f32 v6, v6, v7, v9
	v_div_fixup_f32 v4, v6, v5, v215
	ds_write_b32 v2, v4 offset:19456
	s_waitcnt vmcnt(15)
	v_mul_f32_e32 v5, 0xbfb8aa3b, v216
	v_exp_f32_e32 v5, v5
	s_nop 0
	v_add_f32_e32 v5, 1.0, v5
	v_div_scale_f32 v6, s[88:89], v5, v5, v216
	v_rcp_f32_e32 v7, v6
	v_div_scale_f32 v8, vcc, v216, v5, v216
	v_fma_f32 v9, -v6, v7, 1.0
	v_fmac_f32_e32 v7, v9, v7
	v_mul_f32_e32 v9, v8, v7
	v_fma_f32 v10, -v6, v9, v8
	v_fmac_f32_e32 v9, v10, v7
	v_fma_f32 v6, -v6, v9, v8
	v_div_fmas_f32 v6, v6, v7, v9
	v_div_fixup_f32 v4, v6, v5, v216
	ds_write_b32 v2, v4 offset:20480
	s_waitcnt vmcnt(14)
	v_mul_f32_e32 v5, 0xbfb8aa3b, v217
	v_exp_f32_e32 v5, v5
	s_nop 0
	v_add_f32_e32 v5, 1.0, v5
	v_div_scale_f32 v6, s[88:89], v5, v5, v217
	v_rcp_f32_e32 v7, v6
	v_div_scale_f32 v8, vcc, v217, v5, v217
	v_fma_f32 v9, -v6, v7, 1.0
	v_fmac_f32_e32 v7, v9, v7
	v_mul_f32_e32 v9, v8, v7
	v_fma_f32 v10, -v6, v9, v8
	v_fmac_f32_e32 v9, v10, v7
	v_fma_f32 v6, -v6, v9, v8
	v_div_fmas_f32 v6, v6, v7, v9
	v_div_fixup_f32 v4, v6, v5, v217
	ds_write_b32 v2, v4 offset:21504
	s_waitcnt vmcnt(13)
	v_mul_f32_e32 v5, 0xbfb8aa3b, v218
	v_exp_f32_e32 v5, v5
	s_nop 0
	v_add_f32_e32 v5, 1.0, v5
	v_div_scale_f32 v6, s[88:89], v5, v5, v218
	v_rcp_f32_e32 v7, v6
	v_div_scale_f32 v8, vcc, v218, v5, v218
	v_fma_f32 v9, -v6, v7, 1.0
	v_fmac_f32_e32 v7, v9, v7
	v_mul_f32_e32 v9, v8, v7
	v_fma_f32 v10, -v6, v9, v8
	v_fmac_f32_e32 v9, v10, v7
	v_fma_f32 v6, -v6, v9, v8
	v_div_fmas_f32 v6, v6, v7, v9
	v_div_fixup_f32 v4, v6, v5, v218
	ds_write_b32 v2, v4 offset:22528
	s_waitcnt vmcnt(12)
	v_mul_f32_e32 v5, 0xbfb8aa3b, v219
	v_exp_f32_e32 v5, v5
	s_nop 0
	v_add_f32_e32 v5, 1.0, v5
	v_div_scale_f32 v6, s[88:89], v5, v5, v219
	v_rcp_f32_e32 v7, v6
	v_div_scale_f32 v8, vcc, v219, v5, v219
	v_fma_f32 v9, -v6, v7, 1.0
	v_fmac_f32_e32 v7, v9, v7
	v_mul_f32_e32 v9, v8, v7
	v_fma_f32 v10, -v6, v9, v8
	v_fmac_f32_e32 v9, v10, v7
	v_fma_f32 v6, -v6, v9, v8
	v_div_fmas_f32 v6, v6, v7, v9
	v_div_fixup_f32 v4, v6, v5, v219
	ds_write_b32 v2, v4 offset:23552
	s_waitcnt vmcnt(11)
	v_mul_f32_e32 v5, 0xbfb8aa3b, v220
	v_exp_f32_e32 v5, v5
	s_nop 0
	v_add_f32_e32 v5, 1.0, v5
	v_div_scale_f32 v6, s[88:89], v5, v5, v220
	v_rcp_f32_e32 v7, v6
	v_div_scale_f32 v8, vcc, v220, v5, v220
	v_fma_f32 v9, -v6, v7, 1.0
	v_fmac_f32_e32 v7, v9, v7
	v_mul_f32_e32 v9, v8, v7
	v_fma_f32 v10, -v6, v9, v8
	v_fmac_f32_e32 v9, v10, v7
	v_fma_f32 v6, -v6, v9, v8
	v_div_fmas_f32 v6, v6, v7, v9
	v_div_fixup_f32 v4, v6, v5, v220
	ds_write_b32 v2, v4 offset:24576
	s_waitcnt vmcnt(10)
	v_mul_f32_e32 v5, 0xbfb8aa3b, v221
	v_exp_f32_e32 v5, v5
	s_nop 0
	v_add_f32_e32 v5, 1.0, v5
	v_div_scale_f32 v6, s[88:89], v5, v5, v221
	v_rcp_f32_e32 v7, v6
	v_div_scale_f32 v8, vcc, v221, v5, v221
	v_fma_f32 v9, -v6, v7, 1.0
	v_fmac_f32_e32 v7, v9, v7
	v_mul_f32_e32 v9, v8, v7
	v_fma_f32 v10, -v6, v9, v8
	v_fmac_f32_e32 v9, v10, v7
	v_fma_f32 v6, -v6, v9, v8
	v_div_fmas_f32 v6, v6, v7, v9
	v_div_fixup_f32 v4, v6, v5, v221
	ds_write_b32 v2, v4 offset:25600
	s_waitcnt vmcnt(9)
	v_mul_f32_e32 v5, 0xbfb8aa3b, v222
	v_exp_f32_e32 v5, v5
	s_nop 0
	v_add_f32_e32 v5, 1.0, v5
	v_div_scale_f32 v6, s[88:89], v5, v5, v222
	v_rcp_f32_e32 v7, v6
	v_div_scale_f32 v8, vcc, v222, v5, v222
	v_fma_f32 v9, -v6, v7, 1.0
	v_fmac_f32_e32 v7, v9, v7
	v_mul_f32_e32 v9, v8, v7
	v_fma_f32 v10, -v6, v9, v8
	v_fmac_f32_e32 v9, v10, v7
	v_fma_f32 v6, -v6, v9, v8
	v_div_fmas_f32 v6, v6, v7, v9
	v_div_fixup_f32 v4, v6, v5, v222
	ds_write_b32 v2, v4 offset:26624
	s_waitcnt vmcnt(8)
; DI float siluf_(float z) { return z / (1.f + __expf(-z)); }
; DI void ph_prep(const Params& p, unsigned char* smem, int bid, int nb) {
;     ...
;       for (int e = tid; e < 9 * 1024; e += 256) {
;         const int rr = e >> 10, k = e & 1023;
;         const float v = rr < 8 ? p.c[rr * 1024 + k] : p.c_ctx[k];
;         sc[e] = siluf_(v);
;       }
	v_mul_f32_e32 v5, 0xbfb8aa3b, v223
	v_exp_f32_e32 v5, v5
	s_nop 0
	v_add_f32_e32 v5, 1.0, v5
	v_div_scale_f32 v6, s[88:89], v5, v5, v223
	v_rcp_f32_e32 v7, v6
	v_div_scale_f32 v8, vcc, v223, v5, v223
	v_fma_f32 v9, -v6, v7, 1.0
	v_fmac_f32_e32 v7, v9, v7
	v_mul_f32_e32 v9, v8, v7
	v_fma_f32 v10, -v6, v9, v8
	v_fmac_f32_e32 v9, v10, v7
	v_fma_f32 v6, -v6, v9, v8
	v_div_fmas_f32 v6, v6, v7, v9
	v_div_fixup_f32 v4, v6, v5, v223
	ds_write_b32 v2, v4 offset:27648
	s_waitcnt vmcnt(7)
	v_mul_f32_e32 v5, 0xbfb8aa3b, v224
	v_exp_f32_e32 v5, v5
	s_nop 0
	v_add_f32_e32 v5, 1.0, v5
	v_div_scale_f32 v6, s[88:89], v5, v5, v224
	v_rcp_f32_e32 v7, v6
	v_div_scale_f32 v8, vcc, v224, v5, v224
	v_fma_f32 v9, -v6, v7, 1.0
	v_fmac_f32_e32 v7, v9, v7
	v_mul_f32_e32 v9, v8, v7
	v_fma_f32 v10, -v6, v9, v8
	v_fmac_f32_e32 v9, v10, v7
	v_fma_f32 v6, -v6, v9, v8
	v_div_fmas_f32 v6, v6, v7, v9
	v_div_fixup_f32 v4, v6, v5, v224
	ds_write_b32 v2, v4 offset:28672
	s_waitcnt vmcnt(6)
	v_mul_f32_e32 v5, 0xbfb8aa3b, v225
	v_exp_f32_e32 v5, v5
	s_nop 0
	v_add_f32_e32 v5, 1.0, v5
	v_div_scale_f32 v6, s[88:89], v5, v5, v225
	v_rcp_f32_e32 v7, v6
	v_div_scale_f32 v8, vcc, v225, v5, v225
	v_fma_f32 v9, -v6, v7, 1.0
	v_fmac_f32_e32 v7, v9, v7
	v_mul_f32_e32 v9, v8, v7
	v_fma_f32 v10, -v6, v9, v8
	v_fmac_f32_e32 v9, v10, v7
	v_fma_f32 v6, -v6, v9, v8
	v_div_fmas_f32 v6, v6, v7, v9
	v_div_fixup_f32 v4, v6, v5, v225
	ds_write_b32 v2, v4 offset:29696
	s_waitcnt vmcnt(5)
	v_mul_f32_e32 v5, 0xbfb8aa3b, v226
	v_exp_f32_e32 v5, v5
	s_nop 0
	v_add_f32_e32 v5, 1.0, v5
	v_div_scale_f32 v6, s[88:89], v5, v5, v226
	v_rcp_f32_e32 v7, v6
	v_div_scale_f32 v8, vcc, v226, v5, v226
	v_fma_f32 v9, -v6, v7, 1.0
	v_fmac_f32_e32 v7, v9, v7
	v_mul_f32_e32 v9, v8, v7
	v_fma_f32 v10, -v6, v9, v8
	v_fmac_f32_e32 v9, v10, v7
	v_fma_f32 v6, -v6, v9, v8
	v_div_fmas_f32 v6, v6, v7, v9
	v_div_fixup_f32 v4, v6, v5, v226
	ds_write_b32 v2, v4 offset:30720
	s_waitcnt vmcnt(4)
	v_mul_f32_e32 v5, 0xbfb8aa3b, v227
	v_exp_f32_e32 v5, v5
	s_nop 0
	v_add_f32_e32 v5, 1.0, v5
	v_div_scale_f32 v6, s[88:89], v5, v5, v227
	v_rcp_f32_e32 v7, v6
	v_div_scale_f32 v8, vcc, v227, v5, v227
	v_fma_f32 v9, -v6, v7, 1.0
	v_fmac_f32_e32 v7, v9, v7
	v_mul_f32_e32 v9, v8, v7
	v_fma_f32 v10, -v6, v9, v8
	v_fmac_f32_e32 v9, v10, v7
	v_fma_f32 v6, -v6, v9, v8
	v_div_fmas_f32 v6, v6, v7, v9
	v_div_fixup_f32 v4, v6, v5, v227
	ds_write_b32 v2, v4 offset:31744
	s_waitcnt vmcnt(3)
	v_mul_f32_e32 v5, 0xbfb8aa3b, v228
	v_exp_f32_e32 v5, v5
	s_nop 0
	v_add_f32_e32 v5, 1.0, v5
	v_div_scale_f32 v6, s[88:89], v5, v5, v228
	v_rcp_f32_e32 v7, v6
	v_div_scale_f32 v8, vcc, v228, v5, v228
	v_fma_f32 v9, -v6, v7, 1.0
	v_fmac_f32_e32 v7, v9, v7
	v_mul_f32_e32 v9, v8, v7
	v_fma_f32 v10, -v6, v9, v8
	v_fmac_f32_e32 v9, v10, v7
	v_fma_f32 v6, -v6, v9, v8
	v_div_fmas_f32 v6, v6, v7, v9
	v_div_fixup_f32 v4, v6, v5, v228
	ds_write_b32 v2, v4 offset:32768
	s_waitcnt vmcnt(2)
	v_mul_f32_e32 v5, 0xbfb8aa3b, v229
	v_exp_f32_e32 v5, v5
	s_nop 0
	v_add_f32_e32 v5, 1.0, v5
	v_div_scale_f32 v6, s[88:89], v5, v5, v229
	v_rcp_f32_e32 v7, v6
	v_div_scale_f32 v8, vcc, v229, v5, v229
	v_fma_f32 v9, -v6, v7, 1.0
	v_fmac_f32_e32 v7, v9, v7
	v_mul_f32_e32 v9, v8, v7
	v_fma_f32 v10, -v6, v9, v8
	v_fmac_f32_e32 v9, v10, v7
	v_fma_f32 v6, -v6, v9, v8
	v_div_fmas_f32 v6, v6, v7, v9
	v_div_fixup_f32 v4, v6, v5, v229
	ds_write_b32 v2, v4 offset:33792
	s_waitcnt vmcnt(1)
	v_mul_f32_e32 v5, 0xbfb8aa3b, v230
	v_exp_f32_e32 v5, v5
	s_nop 0
	v_add_f32_e32 v5, 1.0, v5
	v_div_scale_f32 v6, s[88:89], v5, v5, v230
	v_rcp_f32_e32 v7, v6
	v_div_scale_f32 v8, vcc, v230, v5, v230
	v_fma_f32 v9, -v6, v7, 1.0
	v_fmac_f32_e32 v7, v9, v7
	v_mul_f32_e32 v9, v8, v7
	v_fma_f32 v10, -v6, v9, v8
	v_fmac_f32_e32 v9, v10, v7
	v_fma_f32 v6, -v6, v9, v8
	v_div_fmas_f32 v6, v6, v7, v9
	v_div_fixup_f32 v4, v6, v5, v230
	ds_write_b32 v2, v4 offset:34816
	s_waitcnt vmcnt(0)
	v_mul_f32_e32 v5, 0xbfb8aa3b, v231
	v_exp_f32_e32 v5, v5
	s_nop 0
	v_add_f32_e32 v5, 1.0, v5
	v_div_scale_f32 v6, s[88:89], v5, v5, v231
	v_rcp_f32_e32 v7, v6
	v_div_scale_f32 v8, vcc, v231, v5, v231
	v_fma_f32 v9, -v6, v7, 1.0
	v_fmac_f32_e32 v7, v9, v7
	v_mul_f32_e32 v9, v8, v7
	v_fma_f32 v10, -v6, v9, v8
	v_fmac_f32_e32 v9, v10, v7
	v_fma_f32 v6, -v6, v9, v8
	v_div_fmas_f32 v6, v6, v7, v9
	v_div_fixup_f32 v4, v6, v5, v231
	ds_write_b32 v2, v4 offset:35840
